# DIFF: V-fragment ring fill hoisted above the exp lumps, next-tile summary prefetched into SGPRs
# baseline (speedup 1.0000x reference)
; DI u32 pk2(float a, float b) { f2_t v = {a, b}; bf2_t r = __builtin_convertvector(v, bf2_t); return __builtin_bit_cast(u32, r); }
; DI float bflo(u32 u) { return __uint_as_float(u << 16); }
; DI float bfhi(u32 u) { return __uint_as_float(u & 0xffff0000u); }
; DI float xor32_sum(float v) { auto rr = __builtin_amdgcn_permlane32_swap(__float_as_uint(v), __float_as_uint(v), false, false); return __uint_as_float(rr[0]) + __uint_as_float(rr[1]); }
; template <bool DIFF>
; DI void attn_phase(const AttnArgs& a, char* lds) {
;     ...
;       if (DIFF) {
;         float ss = 0.f;
; #pragma unroll
;         for (int ds = 0; ds < NDS; ++ds) {
;           const u32x4 w = __builtin_bit_cast(u32x4, qf[ds]);
; #pragma unroll
;           for (int i = 0; i < 4; ++i) { const float x0 = bflo(w[i]), x1 = bfhi(w[i]); ss += x0 * x0 + x1 * x1; }
;         }
;         ss = xor32_sum(ss);
;         const float ri = rsqrtf(ss * (1.0f / 128.0f) + EPS) * QSCALE_B;
; #pragma unroll
;         for (int ds = 0; ds < NDS; ++ds) {
;           const u32x4 w = __builtin_bit_cast(u32x4, qf[ds]);
;           const float4 ga = *(const float4*)(a.qgain + ds * 16 + (tq >> 5) * 8), gb = *(const float4*)(a.qgain + ds * 16 + (tq >> 5) * 8 + 4);
;           u32x4 o4;
;           o4[0] = pk2(bflo(w[0]) * ri * ga.x, bfhi(w[0]) * ri * ga.y); o4[1] = pk2(bflo(w[1]) * ri * ga.z, bfhi(w[1]) * ri * ga.w);
;           o4[2] = pk2(bflo(w[2]) * ri * gb.x, bfhi(w[2]) * ri * gb.y); o4[3] = pk2(bflo(w[3]) * ri * gb.z, bfhi(w[3]) * ri * gb.w);
;           qf[ds] = __builtin_bit_cast(bf16x8, o4);
;         }
;       }
.LBB0_597:
	s_andn2_b64 vcc, exec, s[66:67]
	s_waitcnt vmcnt(0) lgkmcnt(0)
	s_barrier
	s_cbranch_vccnz .LBB0_630
	v_add_f32_e32 v0, v136, v87
	v_fmamk_f32 v0, v0, 0x3c000000, v212
	v_mul_f32_e32 v87, 0x4b800000, v0
	v_cmp_gt_f32_e32 vcc, s72, v0
	v_mov_b32_e32 v89, v95
	v_mov_b32_e32 v95, v117
	v_cndmask_b32_e32 v0, v0, v87, vcc
	v_rsq_f32_e32 v0, v0
	v_mov_b32_e32 v87, v97
	v_mov_b32_e32 v97, v119
	v_mov_b32_e32 v91, v93
	v_mul_f32_e32 v116, 0x45800000, v0
	v_cndmask_b32_e32 v0, v0, v116, vcc
	v_mul_f32_e32 v0, 0x3e0293ee, v0
	v_pk_mul_f32 v[116:117], v[0:1], v[134:135] op_sel_hi:[0,1]
	v_pk_mul_f32 v[62:63], v[62:63], v[116:117]
	v_mov_b32_e32 v93, v123
	v_cvt_pk_bf16_f32 v176, v62, v63
	v_pk_mul_f32 v[62:63], v[0:1], v[132:133] op_sel_hi:[0,1]
	v_pk_mul_f32 v[62:63], v[64:65], v[62:63]
	s_add_i32 s4, s0, 1
	v_cvt_pk_bf16_f32 v177, v62, v63
	v_pk_mul_f32 v[62:63], v[0:1], v[130:131] op_sel_hi:[0,1]
	v_pk_mul_f32 v[58:59], v[58:59], v[62:63]
	v_cvt_f32_i32_e32 v221, v138
	v_cvt_pk_bf16_f32 v178, v58, v59
	v_pk_mul_f32 v[58:59], v[0:1], v[128:129] op_sel_hi:[0,1]
	v_pk_mul_f32 v[58:59], v[60:61], v[58:59]
	v_cndmask_b32_e64 v222, 0, 1, s[8:9]
	v_cvt_pk_bf16_f32 v179, v58, v59
	v_pk_mul_f32 v[58:59], v[0:1], v[126:127] op_sel_hi:[0,1]
	v_pk_mul_f32 v[54:55], v[54:55], v[58:59]
	v_cndmask_b32_e64 v225, v215, 0, s[8:9]
	v_cvt_pk_bf16_f32 v180, v54, v55
	v_pk_mul_f32 v[54:55], v[0:1], v[124:125] op_sel_hi:[0,1]
	v_pk_mul_f32 v[54:55], v[56:57], v[54:55]
	v_mov_b32_e32 v226, 0
	v_cvt_pk_bf16_f32 v181, v54, v55
	v_pk_mul_f32 v[54:55], v[0:1], v[120:121] op_sel_hi:[0,1]
	v_pk_mul_f32 v[50:51], v[54:55], v[50:51]
	s_nop 0
	v_cvt_pk_bf16_f32 v182, v50, v51
	v_pk_mul_f32 v[50:51], v[0:1], v[66:67] op_sel_hi:[0,1]
	v_pk_mul_f32 v[50:51], v[50:51], v[52:53]
	s_nop 0
	v_cvt_pk_bf16_f32 v183, v50, v51
	v_pk_mul_f32 v[50:51], v[0:1], v[114:115] op_sel_hi:[0,1]
	v_pk_mul_f32 v[46:47], v[50:51], v[46:47]
	s_nop 0
	v_cvt_pk_bf16_f32 v184, v46, v47
	v_pk_mul_f32 v[46:47], v[0:1], v[68:69] op_sel_hi:[0,1]
	v_pk_mul_f32 v[46:47], v[46:47], v[48:49]
	s_nop 0
	v_cvt_pk_bf16_f32 v185, v46, v47
	v_pk_mul_f32 v[46:47], v[0:1], v[112:113] op_sel_hi:[0,1]
	v_pk_mul_f32 v[42:43], v[46:47], v[42:43]
	s_nop 0
	v_cvt_pk_bf16_f32 v186, v42, v43
	v_pk_mul_f32 v[42:43], v[0:1], v[70:71] op_sel_hi:[0,1]
	v_pk_mul_f32 v[42:43], v[42:43], v[44:45]
	s_nop 0
	v_cvt_pk_bf16_f32 v187, v42, v43
	v_pk_mul_f32 v[42:43], v[0:1], v[110:111] op_sel_hi:[0,1]
	v_pk_mul_f32 v[38:39], v[42:43], v[38:39]
	s_nop 0
	v_cvt_pk_bf16_f32 v188, v38, v39
	v_pk_mul_f32 v[38:39], v[0:1], v[72:73] op_sel_hi:[0,1]
	v_pk_mul_f32 v[38:39], v[38:39], v[40:41]
	s_nop 0
	v_cvt_pk_bf16_f32 v189, v38, v39
	v_pk_mul_f32 v[38:39], v[0:1], v[108:109] op_sel_hi:[0,1]
	v_pk_mul_f32 v[34:35], v[38:39], v[34:35]
	s_nop 0
	v_cvt_pk_bf16_f32 v190, v34, v35
	v_pk_mul_f32 v[34:35], v[0:1], v[74:75] op_sel_hi:[0,1]
	v_pk_mul_f32 v[34:35], v[34:35], v[36:37]
	s_nop 0
	v_cvt_pk_bf16_f32 v191, v34, v35
	v_pk_mul_f32 v[34:35], v[0:1], v[106:107] op_sel_hi:[0,1]
	v_pk_mul_f32 v[30:31], v[34:35], v[30:31]
	s_nop 0
	v_cvt_pk_bf16_f32 v192, v30, v31
	v_pk_mul_f32 v[30:31], v[0:1], v[76:77] op_sel_hi:[0,1]
	v_pk_mul_f32 v[30:31], v[30:31], v[32:33]
	s_nop 0
	v_cvt_pk_bf16_f32 v193, v30, v31
	v_pk_mul_f32 v[30:31], v[0:1], v[104:105] op_sel_hi:[0,1]
	v_pk_mul_f32 v[26:27], v[30:31], v[26:27]
	s_nop 0
	v_cvt_pk_bf16_f32 v194, v26, v27
	v_pk_mul_f32 v[26:27], v[0:1], v[78:79] op_sel_hi:[0,1]
	v_pk_mul_f32 v[26:27], v[26:27], v[28:29]
	s_nop 0
	v_cvt_pk_bf16_f32 v195, v26, v27
	v_pk_mul_f32 v[26:27], v[0:1], v[102:103] op_sel_hi:[0,1]
	v_pk_mul_f32 v[22:23], v[26:27], v[22:23]
	s_nop 0
	v_cvt_pk_bf16_f32 v196, v22, v23
	v_pk_mul_f32 v[22:23], v[0:1], v[80:81] op_sel_hi:[0,1]
	v_pk_mul_f32 v[22:23], v[22:23], v[24:25]
	s_nop 0
	v_cvt_pk_bf16_f32 v197, v22, v23
	v_pk_mul_f32 v[22:23], v[0:1], v[100:101] op_sel_hi:[0,1]
	v_pk_mul_f32 v[18:19], v[22:23], v[18:19]
	s_nop 0
	v_cvt_pk_bf16_f32 v198, v18, v19
	v_pk_mul_f32 v[18:19], v[0:1], v[82:83] op_sel_hi:[0,1]
	v_pk_mul_f32 v[18:19], v[18:19], v[20:21]
	s_nop 0
	v_cvt_pk_bf16_f32 v199, v18, v19
	v_pk_mul_f32 v[18:19], v[0:1], v[98:99] op_sel_hi:[0,1]
	v_pk_mul_f32 v[14:15], v[18:19], v[14:15]
	s_nop 0
	v_cvt_pk_bf16_f32 v200, v14, v15
	v_pk_mul_f32 v[14:15], v[0:1], v[84:85] op_sel_hi:[0,1]
	v_pk_mul_f32 v[14:15], v[14:15], v[16:17]
	s_nop 0
	v_cvt_pk_bf16_f32 v201, v14, v15
	v_pk_mul_f32 v[14:15], v[0:1], v[96:97] op_sel_hi:[0,1]
	v_pk_mul_f32 v[10:11], v[14:15], v[10:11]
	v_mov_b32_e32 v14, v1
	v_cvt_pk_bf16_f32 v202, v10, v11
	v_pk_mul_f32 v[10:11], v[0:1], v[86:87] op_sel_hi:[0,1]
	v_pk_mul_f32 v[10:11], v[10:11], v[12:13]
	v_mov_b32_e32 v15, v1
	v_cvt_pk_bf16_f32 v203, v10, v11
	v_pk_mul_f32 v[10:11], v[0:1], v[94:95] op_sel_hi:[0,1]
	v_pk_mul_f32 v[6:7], v[10:11], v[6:7]
; #define GLDS16(g, l) __builtin_amdgcn_global_load_lds((const unsigned*)(g), (unsigned*)(l), 16, 0, 0)
; #define GLDS4(g, l) __builtin_amdgcn_global_load_lds((const unsigned*)(g), (unsigned*)(l), 4, 0, 0)
; DI int tid_pinned() { int t = threadIdx.x; asm volatile("" : "+v"(t)); return t; }
; template <bool DIFF>
; DI void attn_phase(const AttnArgs& a, char* lds) {
;     ...
;     const float slope2 = DIFF ? exp2f(-(float)(h + 1)) * LOG2E : 0.f;
;     ...
;     f32x16 o[NM];
; #pragma unroll
;     for (int m = 0; m < NM; ++m)
; #pragma unroll
;       for (int r = 0; r < 16; ++r) o[m][r] = 0.f;
;     const float sbound = a.lamtab_all[DIFF ? 4 : 3];
;     const int usefix_i = __builtin_amdgcn_readfirstlane(sbound < 40.0f ? 1 : 0);
;     const bool usefix = usefix_i != 0;
;     float m_ref = usefix ? 0.f : -1e30f, l_sum = 0.f;
;     f32x16 negm;
; #pragma unroll
;     for (int r = 0; r < 16; ++r) negm[r] = 0.f;
;     if (t_beg < t_end) {
;       const int t2 = tid_pinned();
;       char* pb = lds + (t_beg & 1) * STAGE;
;       const u32 kofs = KOFS(t2) + (u32)t_beg * 64u * (u32)a.ldk, vofs = VOFS(t2) + (u32)t_beg * (u32)(DV * 64);
; #pragma unroll
;       for (int i = 0; i < NKR; ++i) GLDS16(a.K + kofs + i * 64, pb + wave * 1024 + 8192 * i);
; #pragma unroll
;       for (int i = 0; i < NVR; ++i) GLDS16(a.VT + vofs + i * 4096, pb + KBYTES + wave * 1024 + 8192 * i);
;       if (wave == 0) { const int l4 = t_beg * 64 + (t2 & 63); GLDS4(a.pos + l4, pb + KBYTES + VBYTES); GLDS4(a.posf + l4, pb + KBYTES + VBYTES + 256); }
;     }
;     __syncthreads();
; #pragma unroll 1
;     for (int t = t_beg; t < t_end; ++t) {
;       const char* sb = lds + (t & 1) * STAGE;
;       char* nb = lds + ((t + 1) & 1) * STAGE;
;       const bool nxt = t + 1 < t_end;
;       const int4 tinfo = *(const int4*)(ttab + 4 * t);
;       const int kcmin = __builtin_amdgcn_readfirstlane(tinfo.x), kcmax = __builtin_amdgcn_readfirstlane(tinfo.y);
;       bool skip = kcmin > wqcmax;
;       if (DIFF) {
;         const int tpmin = __builtin_amdgcn_readfirstlane(tinfo.z), tpmax = __builtin_amdgcn_readfirstlane(tinfo.w);
;         const int dist = max(0, max(wpmin - tpmax, tpmin - wpmax));
;         skip = skip || (slope2 * (float)dist > lim2);
;       }
;       const bool needmask = kcmax > wqcmin;
	v_mov_b32_e32 v10, v1
	v_cvt_pk_bf16_f32 v204, v6, v7
	v_pk_mul_f32 v[6:7], v[0:1], v[88:89] op_sel_hi:[0,1]
	v_pk_mul_f32 v[6:7], v[6:7], v[8:9]
	v_mov_b32_e32 v8, v1
	v_cvt_pk_bf16_f32 v205, v6, v7
	v_pk_mul_f32 v[6:7], v[0:1], v[92:93] op_sel_hi:[0,1]
	v_pk_mul_f32 v[2:3], v[6:7], v[2:3]
	v_cvt_f32_i32_e32 v6, s4
	v_cvt_pk_bf16_f32 v206, v2, v3
	v_pk_mul_f32 v[2:3], v[0:1], v[90:91] op_sel_hi:[0,1]
	v_pk_mul_f32 v[2:3], v[2:3], v[4:5]
	v_cmp_lt_f32_e32 vcc, s73, v6
	s_and_b64 s[4:5], vcc, exec
	s_cselect_b32 s4, 0xffffffc0, 0
	v_cndmask_b32_e32 v0, 0, v214, vcc
	v_sub_f32_e32 v0, v0, v6
	v_exp_f32_e32 v0, v0
	s_lshl_b32 s0, s0, 22
	v_cvt_pk_bf16_f32 v207, v2, v3
	v_mov_b32_e32 v2, v1
	v_ldexp_f32 v0, v0, s4
	v_mul_f32_e32 v223, 0x3fb8aa3b, v0
	v_cvt_i32_f32_e32 v0, v221
	s_lshl_b32 s4, s1, 4
	s_add_i32 s80, s4, 0x20ff0
	s_lshl_b32 s4, s1, 6
	s_add_i32 s81, s4, 64
	s_lshl_b32 s4, s1, 14
	v_ashrrev_i32_e32 v224, 6, v0
	s_add_i32 s0, s0, s4
	v_mov_b32_e32 v0, v1
	v_mov_b32_e32 v3, v1
	v_mov_b32_e32 v4, v1
	v_mov_b32_e32 v5, v1
	v_mov_b32_e32 v6, v1
	v_mov_b32_e32 v7, v1
	v_mov_b32_e32 v9, v1
	v_mov_b32_e32 v11, v1
	v_mov_b32_e32 v12, v1
	v_mov_b32_e32 v13, v1
	v_mov_b64_e32 v[30:31], v[14:15]
	v_mov_b64_e32 v[46:47], v[14:15]
	v_mov_b64_e32 v[62:63], v[14:15]
	v_mov_b64_e32 v[78:79], v[14:15]
	v_mov_b64_e32 v[94:95], v[14:15]
	v_mov_b64_e32 v[110:111], v[14:15]
	v_mov_b64_e32 v[126:127], v[14:15]
	v_mov_b64_e32 v[142:143], v[14:15]
	s_add_i32 s79, s75, 0x800
	s_add_i32 s82, s0, 0x4000
	v_mov_b64_e32 v[28:29], v[12:13]
	v_mov_b64_e32 v[26:27], v[10:11]
	v_mov_b64_e32 v[24:25], v[8:9]
	v_mov_b64_e32 v[22:23], v[6:7]
	v_mov_b64_e32 v[20:21], v[4:5]
	v_mov_b64_e32 v[18:19], v[2:3]
	v_mov_b64_e32 v[16:17], v[0:1]
	v_mov_b64_e32 v[44:45], v[12:13]
	v_mov_b64_e32 v[42:43], v[10:11]
	v_mov_b64_e32 v[40:41], v[8:9]
	v_mov_b64_e32 v[38:39], v[6:7]
	v_mov_b64_e32 v[36:37], v[4:5]
	v_mov_b64_e32 v[34:35], v[2:3]
	v_mov_b64_e32 v[32:33], v[0:1]
	v_mov_b64_e32 v[60:61], v[12:13]
	v_mov_b64_e32 v[58:59], v[10:11]
	v_mov_b64_e32 v[56:57], v[8:9]
	v_mov_b64_e32 v[54:55], v[6:7]
	v_mov_b64_e32 v[52:53], v[4:5]
	v_mov_b64_e32 v[50:51], v[2:3]
	v_mov_b64_e32 v[48:49], v[0:1]
	v_mov_b64_e32 v[76:77], v[12:13]
	v_mov_b64_e32 v[74:75], v[10:11]
	v_mov_b64_e32 v[72:73], v[8:9]
	v_mov_b64_e32 v[70:71], v[6:7]
	v_mov_b64_e32 v[68:69], v[4:5]
	v_mov_b64_e32 v[66:67], v[2:3]
	v_mov_b64_e32 v[64:65], v[0:1]
	v_mov_b64_e32 v[92:93], v[12:13]
	v_mov_b64_e32 v[90:91], v[10:11]
	v_mov_b64_e32 v[88:89], v[8:9]
	v_mov_b64_e32 v[86:87], v[6:7]
	v_mov_b64_e32 v[84:85], v[4:5]
	v_mov_b64_e32 v[82:83], v[2:3]
	v_mov_b64_e32 v[80:81], v[0:1]
	v_mov_b64_e32 v[108:109], v[12:13]
	v_mov_b64_e32 v[106:107], v[10:11]
	v_mov_b64_e32 v[104:105], v[8:9]
	v_mov_b64_e32 v[102:103], v[6:7]
	v_mov_b64_e32 v[100:101], v[4:5]
	v_mov_b64_e32 v[98:99], v[2:3]
	v_mov_b64_e32 v[96:97], v[0:1]
	v_mov_b64_e32 v[124:125], v[12:13]
	v_mov_b64_e32 v[122:123], v[10:11]
	v_mov_b64_e32 v[120:121], v[8:9]
	v_mov_b64_e32 v[118:119], v[6:7]
	v_mov_b64_e32 v[116:117], v[4:5]
	v_mov_b64_e32 v[114:115], v[2:3]
	v_mov_b64_e32 v[112:113], v[0:1]
	v_mov_b64_e32 v[140:141], v[12:13]
	v_mov_b64_e32 v[138:139], v[10:11]
	v_mov_b64_e32 v[136:137], v[8:9]
	v_mov_b64_e32 v[134:135], v[6:7]
	v_mov_b64_e32 v[132:133], v[4:5]
	v_mov_b64_e32 v[130:131], v[2:3]
	v_mov_b64_e32 v[128:129], v[0:1]
	v_mov_b32_e32 v0, s80
	ds_read_b128 v[2:5], v0
	s_waitcnt lgkmcnt(0)
	v_readfirstlane_b32 s32, v2
	v_readfirstlane_b32 s87, v3
	v_readfirstlane_b32 s88, v4
	v_readfirstlane_b32 s89, v5
.LBB0_599:
	s_add_i32 s83, s1, 1
	s_cmp_ge_i32 s83, s78
	s_cselect_b64 s[66:67], -1, 0
	s_bitcmp1_b32 s83, 0
	s_cselect_b32 s85, 0x10200, 0
	s_add_i32 s86, s85, s33
	s_nop 1
	v_subrev_u32_e32 v0, s89, v219
	v_sub_u32_e32 v2, s88, v217
	v_max3_i32 v0, v0, v2, 0
	v_cvt_f32_u32_e32 v0, v0
	s_bitcmp1_b32 s1, 0
	s_cselect_b32 s84, 0x10200, 0
	s_cmp_gt_i32 s32, s77
	v_mul_f32_e32 v0, v223, v0
	s_cselect_b64 s[0:1], -1, 0
	v_cmp_gt_f32_e32 vcc, v0, v218
	v_mov_b32_e32 v0, v222
	s_or_b64 s[68:69], s[0:1], vcc
	s_nop 0
	v_readfirstlane_b32 s0, v0
	s_cmp_eq_u32 s0, 0
	s_cselect_b64 s[8:9], -1, 0
	s_or_b64 s[8:9], s[8:9], s[68:69]
	s_and_b64 vcc, exec, s[8:9]
	v_cmp_gt_i32_e64 s[8:9], s87, v220
	s_nop 1
	v_cndmask_b32_e64 v0, 0, 1, s[8:9]
	v_cmp_ne_u32_e64 s[8:9], 1, v0
	s_cbranch_vccnz .Ldiff_slow
	s_or_b64 vcc, s[66:67], s[6:7]
	s_and_b64 vcc, exec, vcc
	s_cbranch_vccnz .Ldiff_nw0
	v_and_b32_e32 v0, 63, v208
	v_add_u32_e32 v2, s81, v0
	v_ashrrev_i32_e32 v3, 31, v2
	v_lshlrev_b64 v[2:3], 2, v[2:3]
	v_lshl_add_u64 v[4:5], s[48:49], 0, v[2:3]
	s_add_i32 m0, s85, 0x10000
	v_lshl_add_u64 v[2:3], s[38:39], 0, v[2:3]
	global_load_lds_dword v[2:3], off
	s_add_i32 m0, s85, 0x10100
	s_nop 0
	global_load_lds_dword v[4:5], off

; #define MFMA(a, b, c) __builtin_amdgcn_mfma_f32_32x32x16_bf16((a), (b), (c), 0, 0, 0)
; DI u32 pk2(float a, float b) { f2_t v = {a, b}; bf2_t r = __builtin_convertvector(v, bf2_t); return __builtin_bit_cast(u32, r); }
; #define DIFF_MASK(sv, sub_) do { if (needmask) { _Pragma("unroll") for (int r = 0; r < 16; ++r) { const int kl_ = (sub_) * 32 + ((r < 8) ? (8 * g2 + r) : (16 + 8 * g2 + (r - 8))); \
;           if ((pki[kl_] >> 6) > (((int)qposf) >> 6)) sv[r] = -__builtin_inff(); } } } while (0)
; template <bool DIFF>
; DI void attn_phase(const AttnArgs& a, char* lds) {
;     ...
;           float ps = 0.f;
; #pragma unroll
;           for (int r = 0; r < 16; ++r) { s0[r] = __builtin_amdgcn_exp2f(s0[r]); ps += s0[r]; }
;           l_sum += ps;
;           asm volatile("" : "+v"(l_sum));
; #pragma unroll
;           for (int i = 0; i < NDS; ++i) { __builtin_amdgcn_sched_group_barrier(0x008, 1, 0); __builtin_amdgcn_sched_group_barrier(0x002, 9, 0); }
;         }
;         __builtin_amdgcn_sched_barrier(0);
;         {
;           bf16x8 vf[NM];
; #pragma unroll
;           for (int s2 = 0; s2 < 2; ++s2) {
; #pragma unroll
;             for (int m = 0; m < NM; ++m) vf[m] = *(const bf16x8*)(sb + voffb + m * 4096 + (((2 * s2) ^ vx) << 4));
;             u32x4 pw;
;             pw[0] = pk2(s0[8 * s2], s0[8 * s2 + 1]); pw[1] = pk2(s0[8 * s2 + 2], s0[8 * s2 + 3]);
;             pw[2] = pk2(s0[8 * s2 + 4], s0[8 * s2 + 5]); pw[3] = pk2(s0[8 * s2 + 6], s0[8 * s2 + 7]);
;             const bf16x8 pf = __builtin_bit_cast(bf16x8, pw);
; #pragma unroll
;             for (int m = 0; m < NM; ++m) o[m] = MFMA(vf[m], pf, o[m]);
;           }
;           DIFF_ALIBI(s1, 1);
;           DIFF_MASK(s1, 1);
.LBB0_605:
	v_exp_f32_e32 v170, v160
	v_exp_f32_e32 v171, v161
	v_bitop3_b32 v0, v0, v3, 7 bitop3:0x78
	v_lshlrev_b32_e32 v2, 7, v2
	v_and_b32_e32 v2, 0xf80, v2
	v_add_u32_e32 v160, s84, v2
	v_lshlrev_b32_e32 v161, 4, v0
	v_add_u32_e32 v0, v160, v161
	ds_read_b128 v[228:231], v0 offset:32768
	ds_read_b128 v[232:235], v0 offset:36864
	ds_read_b128 v[236:239], v0 offset:40960
	ds_read_b128 v[240:243], v0 offset:45056
	ds_read_b128 v[244:247], v0 offset:49152
	ds_read_b128 v[248:251], v0 offset:53248
	v_exp_f32_e32 v11, v11
	v_exp_f32_e32 v9, v9
	v_exp_f32_e32 v10, v10
	v_exp_f32_e32 v8, v8
	v_add_f32_e32 v3, 0, v11
	v_exp_f32_e32 v165, v7
	v_add_f32_e32 v3, v9, v3
	v_exp_f32_e32 v166, v6
	v_add_f32_e32 v3, v10, v3
	v_exp_f32_e32 v167, v5
	v_add_f32_e32 v3, v8, v3
	v_exp_f32_e32 v168, v4
	v_add_f32_e32 v3, v165, v3
	v_exp_f32_e32 v164, v164
	v_add_f32_e32 v3, v166, v3
	v_exp_f32_e32 v169, v162
	v_add_f32_e32 v3, v167, v3
	v_add_f32_e32 v3, v168, v3
	v_add_f32_e32 v3, v164, v3
	v_exp_f32_e32 v15, v15
	v_add_f32_e32 v3, v169, v3
	v_exp_f32_e32 v14, v14
	v_add_f32_e32 v3, v170, v3
	v_exp_f32_e32 v172, v13
	v_add_f32_e32 v3, v171, v3
	v_exp_f32_e32 v173, v12
	v_add_f32_e32 v3, v15, v3
	v_add_f32_e32 v3, v14, v3
	v_add_f32_e32 v3, v172, v3
	v_add_f32_e32 v3, v173, v3
	v_add_f32_e32 v162, v226, v3
	v_cvt_pk_bf16_f32 v6, v11, v9
	v_cvt_pk_bf16_f32 v7, v10, v8
	v_cvt_pk_bf16_f32 v8, v165, v166
	v_cvt_pk_bf16_f32 v9, v167, v168
	v_cvt_pk_bf16_f32 v10, v164, v169
	v_cvt_pk_bf16_f32 v11, v170, v171
	v_cvt_pk_bf16_f32 v12, v15, v14
	v_cvt_pk_bf16_f32 v13, v172, v173
	v_add_u32_e32 v14, 0x10180, v227
	v_xad_u32 v15, v161, 32, v160
	ds_read_b128 v[164:167], v14
	ds_read_b128 v[168:171], v14 offset:16
	ds_read_b128 v[172:175], v14 offset:64
	ds_read_b128 v[2:5], v14 offset:80
	s_and_b64 vcc, exec, s[8:9]
	s_waitcnt lgkmcnt(9)
	v_mfma_f32_32x32x16_bf16 v[128:143], v[228:231], v[6:9], v[128:143]
	ds_read_b128 v[228:231], v0 offset:57344
	s_waitcnt lgkmcnt(9)
	v_mfma_f32_32x32x16_bf16 v[112:127], v[232:235], v[6:9], v[112:127]
	ds_read_b128 v[232:235], v0 offset:61440
	s_waitcnt lgkmcnt(9)
	v_mfma_f32_32x32x16_bf16 v[96:111], v[236:239], v[6:9], v[96:111]
	ds_read_b128 v[236:239], v15 offset:32768
	s_waitcnt lgkmcnt(9)
	v_mfma_f32_32x32x16_bf16 v[80:95], v[240:243], v[6:9], v[80:95]
	ds_read_b128 v[240:243], v15 offset:36864
	s_waitcnt lgkmcnt(9)
	v_mfma_f32_32x32x16_bf16 v[64:79], v[244:247], v[6:9], v[64:79]
	ds_read_b128 v[244:247], v15 offset:40960
	s_waitcnt lgkmcnt(9)
	v_mfma_f32_32x32x16_bf16 v[48:63], v[248:251], v[6:9], v[48:63]
	ds_read_b128 v[248:251], v15 offset:45056
	s_waitcnt lgkmcnt(5)
	v_mfma_f32_32x32x16_bf16 v[32:47], v[228:231], v[6:9], v[32:47]
	ds_read_b128 v[228:231], v15 offset:49152
	v_sub_f32_e32 v164, v221, v164
	v_sub_f32_e32 v165, v221, v165
	v_sub_f32_e32 v166, v221, v166
	v_sub_f32_e32 v167, v221, v167
	s_waitcnt lgkmcnt(5)
	v_mfma_f32_32x32x16_bf16 v[16:31], v[232:235], v[6:9], v[16:31]
	ds_read_b128 v[232:235], v15 offset:53248
	v_sub_f32_e32 v168, v221, v168
	v_sub_f32_e32 v169, v221, v169
	v_sub_f32_e32 v170, v221, v170
	v_sub_f32_e32 v171, v221, v171
	s_waitcnt lgkmcnt(5)
	v_mfma_f32_32x32x16_bf16 v[128:143], v[236:239], v[10:13], v[128:143]
	ds_read_b128 v[236:239], v15 offset:57344
	v_sub_f32_e32 v172, v221, v172
	v_sub_f32_e32 v173, v221, v173
	v_sub_f32_e32 v174, v221, v174
	v_sub_f32_e32 v175, v221, v175
	s_waitcnt lgkmcnt(5)
	v_mfma_f32_32x32x16_bf16 v[112:127], v[240:243], v[10:13], v[112:127]
	ds_read_b128 v[240:243], v15 offset:61440
	v_sub_f32_e32 v2, v221, v2
	v_sub_f32_e32 v3, v221, v3
	v_sub_f32_e32 v4, v221, v4
	v_sub_f32_e32 v5, v221, v5
	s_waitcnt lgkmcnt(5)
	v_mfma_f32_32x32x16_bf16 v[96:111], v[244:247], v[10:13], v[96:111]
	v_fma_f32 v164, -v223, |v164|, v144
	v_fma_f32 v165, -v223, |v165|, v145
	v_fma_f32 v166, -v223, |v166|, v146
	v_fma_f32 v167, -v223, |v167|, v147
	s_waitcnt lgkmcnt(4)
	v_mfma_f32_32x32x16_bf16 v[80:95], v[248:251], v[10:13], v[80:95]
	v_fma_f32 v168, -v223, |v168|, v148
	v_fma_f32 v169, -v223, |v169|, v149
	v_fma_f32 v170, -v223, |v170|, v150
	v_fma_f32 v171, -v223, |v171|, v151
	s_waitcnt lgkmcnt(3)
	v_mfma_f32_32x32x16_bf16 v[64:79], v[228:231], v[10:13], v[64:79]
	v_fma_f32 v172, -v223, |v172|, v152
	v_fma_f32 v173, -v223, |v173|, v153
	v_fma_f32 v174, -v223, |v174|, v154
	v_fma_f32 v175, -v223, |v175|, v155
	s_waitcnt lgkmcnt(2)
	v_mfma_f32_32x32x16_bf16 v[48:63], v[232:235], v[10:13], v[48:63]
	v_fma_f32 v2, -v223, |v2|, v156
	v_fma_f32 v3, -v223, |v3|, v157
	v_fma_f32 v4, -v223, |v4|, v158
	v_fma_f32 v5, -v223, |v5|, v159
	s_waitcnt lgkmcnt(1)
	v_mfma_f32_32x32x16_bf16 v[32:47], v[236:239], v[10:13], v[32:47]
	s_waitcnt lgkmcnt(0)
	v_mfma_f32_32x32x16_bf16 v[16:31], v[240:243], v[10:13], v[16:31]
	s_add_i32 s87, s80, 16
	v_mov_b32_e32 v10, s87
	ds_read_b128 v[10:13], v10
	v_xad_u32 v156, v161, 64, v160
	ds_read_b128 v[228:231], v156 offset:32768
	ds_read_b128 v[232:235], v156 offset:36864
	ds_read_b128 v[236:239], v156 offset:40960
	ds_read_b128 v[240:243], v156 offset:45056
	ds_read_b128 v[244:247], v156 offset:49152
	ds_read_b128 v[248:251], v156 offset:53248
	s_cbranch_vccnz .LBB0_607
; #define MFMA(a, b, c) __builtin_amdgcn_mfma_f32_32x32x16_bf16((a), (b), (c), 0, 0, 0)
; DI u32 pk2(float a, float b) { f2_t v = {a, b}; bf2_t r = __builtin_convertvector(v, bf2_t); return __builtin_bit_cast(u32, r); }
; #define DIFF_MASK(sv, sub_) do { if (needmask) { _Pragma("unroll") for (int r = 0; r < 16; ++r) { const int kl_ = (sub_) * 32 + ((r < 8) ? (8 * g2 + r) : (16 + 8 * g2 + (r - 8))); \
;           if ((pki[kl_] >> 6) > (((int)qposf) >> 6)) sv[r] = -__builtin_inff(); } } } while (0)
; template <bool DIFF>
; DI void attn_phase(const AttnArgs& a, char* lds) {
;     ...
;           DIFF_MASK(s1, 1);
;           float ps = 0.f;
; #pragma unroll
;           for (int r = 0; r < 16; ++r) { s1[r] = __builtin_amdgcn_exp2f(s1[r]); ps += s1[r]; }
;           l_sum += ps;
;           asm volatile("" : "+v"(l_sum));
; #pragma unroll
;           for (int i = 0; i < 2 * NM; ++i) { __builtin_amdgcn_sched_group_barrier(0x008, 1, 0); __builtin_amdgcn_sched_group_barrier(0x002, 4, 0); }
;         }
;         __builtin_amdgcn_sched_barrier(0);
;         {
; #pragma unroll
;           for (int s2 = 0; s2 < 2; ++s2) {
;             bf16x8 vf[NM];
; #pragma unroll
;             for (int m = 0; m < NM; ++m) vf[m] = *(const bf16x8*)(sb + voffb + m * 4096 + (((4 + 2 * s2) ^ vx) << 4));
;             u32x4 pw;
;             pw[0] = pk2(s1[8 * s2], s1[8 * s2 + 1]); pw[1] = pk2(s1[8 * s2 + 2], s1[8 * s2 + 3]);
;             pw[2] = pk2(s1[8 * s2 + 4], s1[8 * s2 + 5]); pw[3] = pk2(s1[8 * s2 + 6], s1[8 * s2 + 7]);
;             const bf16x8 pf = __builtin_bit_cast(bf16x8, pw);
; #pragma unroll
;             for (int m = 0; m < NM; ++m) o[m] = MFMA(vf[m], pf, o[m]);
;           }
;         }
	ds_read_b128 v[146:149], v163 offset:128
	s_waitcnt lgkmcnt(0)
	v_ashrrev_i32_e32 v144, 6, v146
	v_cmp_le_i32_e32 vcc, v144, v224
	v_ashrrev_i32_e32 v144, 6, v147
	s_nop 0
	v_cndmask_b32_e32 v164, v216, v164, vcc
	v_cmp_le_i32_e32 vcc, v144, v224
	v_ashrrev_i32_e32 v144, 6, v148
	s_nop 0
	v_cndmask_b32_e32 v165, v216, v165, vcc
	v_cmp_le_i32_e32 vcc, v144, v224
	v_ashrrev_i32_e32 v144, 6, v149
	s_nop 0
	v_cndmask_b32_e32 v166, v216, v166, vcc
	v_cmp_le_i32_e32 vcc, v144, v224
	v_add_u32_e32 v144, 0x10090, v227
	ds_read_b128 v[146:149], v144
	v_cndmask_b32_e32 v167, v216, v167, vcc
	s_waitcnt lgkmcnt(0)
	v_ashrrev_i32_e32 v144, 6, v146
	v_cmp_le_i32_e32 vcc, v144, v224
	v_ashrrev_i32_e32 v144, 6, v147
	s_nop 0
	v_cndmask_b32_e32 v168, v216, v168, vcc
	v_cmp_le_i32_e32 vcc, v144, v224
	v_ashrrev_i32_e32 v144, 6, v148
	s_nop 0
	v_cndmask_b32_e32 v169, v216, v169, vcc
	v_cmp_le_i32_e32 vcc, v144, v224
	v_ashrrev_i32_e32 v144, 6, v149
	s_nop 0
	v_cndmask_b32_e32 v170, v216, v170, vcc
	v_cmp_le_i32_e32 vcc, v144, v224
	v_add_u32_e32 v144, 0x100c0, v227
	ds_read_b128 v[146:149], v144
	v_cndmask_b32_e32 v171, v216, v171, vcc
	s_waitcnt lgkmcnt(0)
	v_ashrrev_i32_e32 v144, 6, v146
	v_cmp_le_i32_e32 vcc, v144, v224
	v_ashrrev_i32_e32 v144, 6, v147
	s_nop 0
	v_cndmask_b32_e32 v172, v216, v172, vcc
	v_cmp_le_i32_e32 vcc, v144, v224
	v_ashrrev_i32_e32 v144, 6, v148
	s_nop 0
	v_cndmask_b32_e32 v173, v216, v173, vcc
	v_cmp_le_i32_e32 vcc, v144, v224
	v_ashrrev_i32_e32 v144, 6, v149
	s_nop 0
	v_cndmask_b32_e32 v174, v216, v174, vcc
	v_cmp_le_i32_e32 vcc, v144, v224
	v_add_u32_e32 v144, 0x100d0, v227
	ds_read_b128 v[146:149], v144
	v_cndmask_b32_e32 v175, v216, v175, vcc
	s_waitcnt lgkmcnt(0)
	v_ashrrev_i32_e32 v144, 6, v146
	v_cmp_le_i32_e32 vcc, v144, v224
	v_ashrrev_i32_e32 v144, 6, v147
	s_nop 0
	v_cndmask_b32_e32 v2, v216, v2, vcc
	v_cmp_le_i32_e32 vcc, v144, v224
	v_ashrrev_i32_e32 v144, 6, v148
	s_nop 0
	v_cndmask_b32_e32 v3, v216, v3, vcc
	v_cmp_le_i32_e32 vcc, v144, v224
	v_ashrrev_i32_e32 v144, 6, v149
	s_nop 0
	v_cndmask_b32_e32 v4, v216, v4, vcc
	v_cmp_le_i32_e32 vcc, v144, v224
	s_nop 1
	v_cndmask_b32_e32 v5, v216, v5, vcc
.LBB0_607:
	v_exp_f32_e32 v0, v164
	v_exp_f32_e32 v9, v165
	v_exp_f32_e32 v144, v166
	v_exp_f32_e32 v146, v167
	v_add_f32_e32 v253, 0, v0
	v_exp_f32_e32 v147, v168
	v_add_f32_e32 v253, v9, v253
	v_exp_f32_e32 v148, v169
	v_add_f32_e32 v253, v144, v253
	v_exp_f32_e32 v149, v170
	v_add_f32_e32 v253, v146, v253
	v_exp_f32_e32 v150, v171
	v_add_f32_e32 v253, v147, v253
	v_exp_f32_e32 v151, v172
	v_add_f32_e32 v253, v148, v253
	v_exp_f32_e32 v145, v173
	v_add_f32_e32 v253, v149, v253
	v_exp_f32_e32 v152, v174
	v_add_f32_e32 v253, v150, v253
	v_exp_f32_e32 v153, v175
	v_add_f32_e32 v253, v151, v253
	v_exp_f32_e32 v154, v2
	v_add_f32_e32 v253, v145, v253
	v_exp_f32_e32 v155, v3
	v_add_f32_e32 v253, v152, v253
	v_exp_f32_e32 v14, v4
	v_add_f32_e32 v253, v153, v253
	v_exp_f32_e32 v15, v5
	v_add_f32_e32 v253, v154, v253
	v_add_f32_e32 v253, v155, v253
	v_add_f32_e32 v253, v14, v253
	v_add_f32_e32 v253, v15, v253
	v_add_f32_e32 v226, v162, v253
	ds_read_b128 v[2:5], v156 offset:57344
	s_waitcnt lgkmcnt(7)
	v_readfirstlane_b32 s32, v10
	v_readfirstlane_b32 s87, v11
	v_readfirstlane_b32 s88, v12
	v_readfirstlane_b32 s89, v13
	v_cvt_pk_bf16_f32 v6, v0, v9
	v_cvt_pk_bf16_f32 v7, v144, v146
	v_cvt_pk_bf16_f32 v8, v147, v148
	v_cvt_pk_bf16_f32 v9, v149, v150
	v_xad_u32 v0, v161, s74, v160
	v_cvt_pk_bf16_f32 v10, v151, v145
	v_cvt_pk_bf16_f32 v11, v152, v153
	v_cvt_pk_bf16_f32 v12, v154, v155
	v_cvt_pk_bf16_f32 v13, v14, v15
	s_waitcnt lgkmcnt(6)
	v_mfma_f32_32x32x16_bf16 v[128:143], v[228:231], v[6:9], v[128:143]
	ds_read_b128 v[228:231], v156 offset:61440
	s_waitcnt lgkmcnt(6)
	v_mfma_f32_32x32x16_bf16 v[112:127], v[232:235], v[6:9], v[112:127]
	ds_read_b128 v[232:235], v0 offset:32768
	s_waitcnt lgkmcnt(6)
	v_mfma_f32_32x32x16_bf16 v[96:111], v[236:239], v[6:9], v[96:111]
	ds_read_b128 v[236:239], v0 offset:36864
	s_waitcnt lgkmcnt(6)
	v_mfma_f32_32x32x16_bf16 v[80:95], v[240:243], v[6:9], v[80:95]
	ds_read_b128 v[240:243], v0 offset:40960
	s_waitcnt lgkmcnt(6)
	v_mfma_f32_32x32x16_bf16 v[64:79], v[244:247], v[6:9], v[64:79]
	ds_read_b128 v[244:247], v0 offset:45056
	s_waitcnt lgkmcnt(6)
	v_mfma_f32_32x32x16_bf16 v[48:63], v[248:251], v[6:9], v[48:63]
	ds_read_b128 v[248:251], v0 offset:49152
	s_waitcnt lgkmcnt(6)
	v_mfma_f32_32x32x16_bf16 v[32:47], v[2:5], v[6:9], v[32:47]
	ds_read_b128 v[2:5], v0 offset:53248
	s_waitcnt lgkmcnt(6)
	v_mfma_f32_32x32x16_bf16 v[16:31], v[228:231], v[6:9], v[16:31]
	ds_read_b128 v[228:231], v0 offset:57344
	s_waitcnt lgkmcnt(6)
	v_mfma_f32_32x32x16_bf16 v[128:143], v[232:235], v[10:13], v[128:143]
	ds_read_b128 v[232:235], v0 offset:61440
	s_waitcnt lgkmcnt(6)
	v_mfma_f32_32x32x16_bf16 v[112:127], v[236:239], v[10:13], v[112:127]
	s_waitcnt lgkmcnt(5)
	v_mfma_f32_32x32x16_bf16 v[96:111], v[240:243], v[10:13], v[96:111]
	s_waitcnt lgkmcnt(4)
	v_mfma_f32_32x32x16_bf16 v[80:95], v[244:247], v[10:13], v[80:95]
	s_waitcnt lgkmcnt(3)
	v_mfma_f32_32x32x16_bf16 v[64:79], v[248:251], v[10:13], v[64:79]
	s_waitcnt lgkmcnt(2)
	v_mfma_f32_32x32x16_bf16 v[48:63], v[2:5], v[10:13], v[48:63]
	s_waitcnt lgkmcnt(1)
	v_mfma_f32_32x32x16_bf16 v[32:47], v[228:231], v[10:13], v[32:47]
	s_waitcnt lgkmcnt(0)
	v_mfma_f32_32x32x16_bf16 v[16:31], v[232:235], v[10:13], v[16:31]

; #define GLDS16(g, l) __builtin_amdgcn_global_load_lds((const unsigned*)(g), (unsigned*)(l), 16, 0, 0)
; #define GLDS4(g, l) __builtin_amdgcn_global_load_lds((const unsigned*)(g), (unsigned*)(l), 4, 0, 0)
; DI int tid_pinned() { int t = threadIdx.x; asm volatile("" : "+v"(t)); return t; }
; template <bool DIFF>
; DI void attn_phase(const AttnArgs& a, char* lds) {
;     ...
;       const int4 tinfo = *(const int4*)(ttab + 4 * t);
;       const int kcmin = __builtin_amdgcn_readfirstlane(tinfo.x), kcmax = __builtin_amdgcn_readfirstlane(tinfo.y);
;       bool skip = kcmin > wqcmax;
;       if (DIFF) {
;         const int tpmin = __builtin_amdgcn_readfirstlane(tinfo.z), tpmax = __builtin_amdgcn_readfirstlane(tinfo.w);
;         const int dist = max(0, max(wpmin - tpmax, tpmin - wpmax));
;         skip = skip || (slope2 * (float)dist > lim2);
;       }
;       const bool needmask = kcmax > wqcmin;
;       if (nxt) {
;         const int t2 = tid_pinned();
;         const u32 kofs = KOFS(t2), vofs = VOFS(t2);
;         const u32 ko2 = kofs + (u32)(t + 1) * 64u * (u32)a.ldk;
; #pragma unroll
;         for (int i = 0; i < NKR; ++i) GLDS16(a.K + ko2 + i * 64, nb + wave * 1024 + 8192 * i);
;         const u32 vo2 = vofs + (u32)(t + 1) * (u32)(DV * 64);
; #pragma unroll
;         for (int i = 0; i < NVR; ++i) GLDS16(a.VT + vo2 + i * 4096, nb + KBYTES + wave * 1024 + 8192 * i);
;         if (wave == 0) { const int l4 = (t + 1) * 64 + (t2 & 63); GLDS4(a.pos + l4, nb + KBYTES + VBYTES); GLDS4(a.posf + l4, nb + KBYTES + VBYTES + 256); }
;       }
.Ldiff_slow:
	s_add_i32 s87, s80, 16
	v_mov_b32_e32 v0, s87
	ds_read_b128 v[2:5], v0
	s_waitcnt lgkmcnt(0)
	v_readfirstlane_b32 s32, v2
	v_readfirstlane_b32 s87, v3
	v_readfirstlane_b32 s88, v4
	v_readfirstlane_b32 s89, v5
	s_and_b64 vcc, exec, s[66:67]
	s_cbranch_vccnz .LBB0_608
	v_mov_b32_e32 v2, v208
	v_lshrrev_b32_e32 v0, 4, v2
	v_xor_b32_e32 v0, v0, v2
	v_ashrrev_i32_e32 v3, 3, v2
	v_lshlrev_b32_e32 v0, 3, v0
	v_and_b32_e32 v8, 56, v0
	v_add_u32_e32 v0, s81, v3
	v_lshl_add_u32 v0, v0, 12, s79
	v_or_b32_e32 v0, v0, v8
	v_lshl_add_u64 v[4:5], v[0:1], 1, s[30:31]
	s_mov_b32 m0, s86
	v_lshl_add_u64 v[6:7], v[4:5], 0, s[42:43]
	global_load_lds_dwordx4 v[4:5], off
	s_add_i32 m0, s86, 0x2000
	v_lshl_or_b32 v0, v3, 6, v8
	global_load_lds_dwordx4 v[6:7], off
	v_lshl_add_u64 v[6:7], v[4:5], 0, s[56:57]
	s_add_i32 m0, s86, 0x4000
	v_lshl_add_u64 v[4:5], v[4:5], 0, s[58:59]
	global_load_lds_dwordx4 v[6:7], off
	s_add_i32 m0, s86, 0x6000
	v_add_u32_e32 v0, s82, v0
	global_load_lds_dwordx4 v[4:5], off
	s_add_i32 m0, s86, 0x8000
	v_lshl_add_u64 v[4:5], v[0:1], 1, s[36:37]
	global_load_lds_dwordx4 v[4:5], off
	v_lshl_add_u64 v[6:7], v[4:5], 0, s[60:61]
	s_add_i32 m0, s86, 0xa000
	s_and_b64 vcc, exec, s[6:7]
	global_load_lds_dwordx4 v[6:7], off
	v_lshl_add_u64 v[6:7], v[4:5], 0, s[62:63]
	s_add_i32 m0, s86, 0xc000
	v_lshl_add_u64 v[4:5], v[4:5], 0, s[64:65]
	global_load_lds_dwordx4 v[6:7], off
	s_add_i32 m0, s86, 0xe000
	s_nop 0
	global_load_lds_dwordx4 v[4:5], off
	s_cbranch_vccnz .LBB0_608
	v_and_b32_e32 v0, 63, v2
	v_add_u32_e32 v2, s81, v0
	v_ashrrev_i32_e32 v3, 31, v2
	v_lshlrev_b64 v[2:3], 2, v[2:3]
	v_lshl_add_u64 v[4:5], s[48:49], 0, v[2:3]
	s_add_i32 m0, s85, 0x10000
	v_lshl_add_u64 v[2:3], s[38:39], 0, v[2:3]
	global_load_lds_dword v[2:3], off
	s_add_i32 m0, s85, 0x10100
	s_nop 0
	global_load_lds_dword v[4:5], off
	s_branch .LBB0_608
